# strategy 9 / guide 7.12: wave-uniform __all ballot in the 3 flash loops trimmed to s_or + s_cmp_eq_u64 (EXEC full), on the packed-op-split stack
# baseline (speedup 1.0000x reference)
; template <int DV, bool FOX>
; DI void flash(f32x16 (&O)[DV / 32], const bf16_t* __restrict__ qptr, const bf16_t* __restrict__ kg, const bf16_t* __restrict__ vtg,
;               int ntiles, int q, float slope2, const float* __restrict__ cum2, float KN, bf16_t* smem) {
;     ...
;         if (kt > 0) {
;             const int klast = kb - 1;
;             float bm = 0.f;
;             if (klast < q) bm = FOX ? cq - cklast : -slope2 * (float)(q - klast);
;             const bool pred = (q >= LT) || (sbound + bm < m - 152.f);
;             wskip = __all(pred);
;         }
.LBB0_626:
	v_subrev_u32_e32 v68, s78, v163
	v_cvt_f32_i32_e32 v68, v68
	v_cmp_le_i32_e32 vcc, s78, v154
	v_mul_f32_e64 v68, -v159, v68
	s_nop 0
	v_cndmask_b32_e32 v142, 0, v68, vcc
	v_add_f32_e64 v68, v172, v142
	v_add_f32_e64 v69, v173, v143
	s_nop 0
	v_cmp_lt_f32_e32 vcc, v68, v69
	s_or_b64 s[10:11], s[4:5], vcc
	s_cmp_eq_u64 s[10:11], exec
	s_cselect_b64 s[10:11], -1, 0

; template <int DV, bool FOX>
; DI void flash(f32x16 (&O)[DV / 32], const bf16_t* __restrict__ qptr, const bf16_t* __restrict__ kg, const bf16_t* __restrict__ vtg,
;               int ntiles, int q, float slope2, const float* __restrict__ cum2, float KN, bf16_t* smem) {
;     ...
;         if (kt > 0) {
;             const int klast = kb - 1;
;             float bm = 0.f;
;             if (klast < q) bm = FOX ? cq - cklast : -slope2 * (float)(q - klast);
;             const bool pred = (q >= LT) || (sbound + bm < m - 152.f);
;             wskip = __all(pred);
;         }
.LBB0_664:
	v_subrev_u32_e32 v68, s68, v163
	v_cvt_f32_i32_e32 v68, v68
	v_cmp_le_i32_e32 vcc, s68, v154
	v_mul_f32_e64 v68, -v159, v68
	s_nop 0
	v_cndmask_b32_e32 v142, 0, v68, vcc
	v_add_f32_e64 v68, v170, v142
	v_add_f32_e64 v69, v171, v143
	s_nop 0
	v_cmp_lt_f32_e32 vcc, v68, v69
	s_or_b64 s[10:11], s[4:5], vcc
	s_cmp_eq_u64 s[10:11], exec
	s_cselect_b64 s[10:11], -1, 0

; template <int DV, bool FOX>
; DI void flash(f32x16 (&O)[DV / 32], const bf16_t* __restrict__ qptr, const bf16_t* __restrict__ kg, const bf16_t* __restrict__ vtg,
;               int ntiles, int q, float slope2, const float* __restrict__ cum2, float KN, bf16_t* smem) {
;     ...
;         if (kt > 0) {
;             const int klast = kb - 1;
;             float bm = 0.f;
;             if (klast < q) bm = FOX ? cq - cklast : -slope2 * (float)(q - klast);
;             const bool pred = (q >= LT) || (sbound + bm < m - 152.f);
;             wskip = __all(pred);
;         }
.LBB0_710:
	s_waitcnt vmcnt(0)
	v_sub_f32_e32 v0, v108, v142
	v_cmp_le_i32_e32 vcc, s70, v154
	s_nop 1
	v_cndmask_b32_e32 v142, 0, v0, vcc
	v_add_f32_e64 v36, v116, v142
	v_add_f32_e64 v37, v117, v143
	s_nop 0
	v_cmp_lt_f32_e32 vcc, v36, v37
	s_or_b64 s[10:11], s[4:5], vcc
	s_cmp_eq_u64 s[10:11], exec
	s_cselect_b64 s[10:11], -1, 0
